# mixer-B loop: one static s_setprio 1 for waves 4-7 before the loop, back to 0 after the last PV
# baseline (speedup 1.0000x reference)
; #define LAS __attribute__((address_space(3)))
; __device__ __forceinline__ float half_max(float v) { auto rr = __builtin_amdgcn_permlane32_swap(__float_as_uint(v), __float_as_uint(v), false, false); return fmaxf(__uint_as_float(rr[0]), __uint_as_float(rr[1])); }
; #define SLOAD(i, k0) do { sr_[i].vs0 = *(const bf16x8*)(Vh + (size_t)((k0) + sr) * PW + sc); sr_[i].vs1 = *(const bf16x8*)(Vh + (size_t)((k0) + 32 + sr) * PW + sc); \
;     sr_[i].ks0 = *(const bf16x8*)(Kh + (size_t)((k0) + sr) * PW + sc); sr_[i].ks1 = *(const bf16x8*)(Kh + (size_t)((k0) + 32 + sr) * PW + sc); } while (0)
; #define SWRITE(b, i) do { *(LAS bf16x8*)(V_lds + (b) * SHM_V + vst0) = sr_[i].vs0; *(LAS bf16x8*)(V_lds + (b) * SHM_V + vst1) = sr_[i].vs1; const int kc = sc * 2; \
;     *(LAS bf16x8*)(K_lds + (b) * SHM_K + KSWZ(sr, kc)) = sr_[i].ks0; *(LAS bf16x8*)(K_lds + (b) * SHM_K + KSWZ(32 + sr, kc)) = sr_[i].ks1; } while (0)
; __device__ __forceinline__ void partialSM(f32x16& p0, f32x16& p1, const LAS float* tbp, int relc, float cL, float cR, float& m_reg, float& mn, float& alpha) {
;     float cb = 0.f;
;     if (relc + 63 <= -559) cb = cL;
;     else if (relc - 31 >= 559) cb = cR;
;     else {
; #pragma unroll
;         for (int r = 0; r < 16; ++r) { p0[r] += tbp[(r & 3) + 8 * (r >> 2)]; p1[r] += tbp[32 + (r & 3) + 8 * (r >> 2)]; }
;     }
;     float pmax = p0[0];
; #pragma unroll
;     for (int r = 1; r < 16; ++r) pmax = fmaxf(pmax, p0[r]);
; #pragma unroll
;     for (int r = 0; r < 16; ++r) pmax = fmaxf(pmax, p1[r]);
;     pmax = half_max(pmax) + cb;
;     if (__builtin_expect(__all(pmax - m_reg <= 8.f), 1)) { mn = m_reg; alpha = 1.f; }
;     else { mn = fmaxf(m_reg, pmax); alpha = __builtin_amdgcn_exp2f(m_reg - mn); m_reg = mn; }
;     const float sh = mn - cb;
; #pragma unroll
;     for (int r = 0; r < 16; ++r) { p0[r] -= sh; p1[r] -= sh; }
; #pragma unroll
;     for (int r = 0; r < 16; ++r) p0[r] = __builtin_amdgcn_exp2f(p0[r]);
; }
; __device__ __forceinline__ void unit(LAS unsigned char* lds, const bf16* __restrict__ PROJ, bf16* __restrict__ MIXED, const float* __restrict__ subln_g, float lam, int R0, int seq, int h, int qb) {
;     ...
;     qkt(pA0, pA1, K_lds, qr, r32, cb0); partialSM(pA0, pA1, tbq, rc0, cL, cR, m_reg, mnA, alA);
;     SLOAD(SO, 64); if (2 < NT) SLOAD(SE, 128);
;     SWAIT(); SWRITE(1, SO); __syncthreads();
.LBB0_259:
	v_add_co_u32_e32 v38, vcc, s54, v32
	s_nop 6
	v_max_f32_e32 v58, v1, v1
	v_addc_co_u32_e32 v39, vcc, 0, v33, vcc
	v_add_co_u32_e32 v42, vcc, s55, v32
	v_max_f32_e32 v59, v0, v0
	s_nop 0
	v_addc_co_u32_e32 v43, vcc, 0, v33, vcc
	v_add_co_u32_e32 v46, vcc, s54, v34
	global_load_dwordx4 v[38:41], v[38:39], off
	s_nop 0
	global_load_dwordx4 v[42:45], v[42:43], off
	v_addc_co_u32_e32 v47, vcc, 0, v35, vcc
	v_add_co_u32_e32 v50, vcc, s55, v34
	v_max_f32_e32 v58, v59, v58
	s_nop 0
	v_addc_co_u32_e32 v51, vcc, 0, v35, vcc
	v_add_co_u32_e32 v54, vcc, s56, v34
	global_load_dwordx4 v[46:49], v[46:47], off
	s_nop 0
	global_load_dwordx4 v[50:53], v[50:51], off
	v_addc_co_u32_e32 v55, vcc, 0, v35, vcc
	v_add_co_u32_e32 v34, vcc, s57, v34
	s_and_b32 s4, s33, 0x3fffffc0
	s_nop 0
	v_addc_co_u32_e32 v35, vcc, 0, v35, vcc
	v_add_co_u32_e32 v56, vcc, s56, v32
	s_lshl_b32 s4, s4, 2
	s_nop 0
	v_addc_co_u32_e32 v57, vcc, 0, v33, vcc
	v_add_co_u32_e32 v32, vcc, s57, v32
	s_add_i32 s4, s4, 0
	s_nop 0
	v_addc_co_u32_e32 v33, vcc, 0, v33, vcc
	global_load_dwordx4 v[116:119], v[54:55], off
	global_load_dwordx4 v[112:115], v[34:35], off
	global_load_dwordx4 v[124:127], v[56:57], off
	global_load_dwordx4 v[120:123], v[32:33], off
	v_max3_f32 v32, v58, v2, v3
	v_max3_f32 v32, v32, v4, v5
	v_max3_f32 v32, v32, v6, v7
	v_max3_f32 v32, v32, v8, v9
	v_max3_f32 v32, v32, v10, v11
	v_max3_f32 v32, v32, v12, v13
	v_max3_f32 v32, v32, v14, v15
	v_max3_f32 v32, v32, v16, v17
	v_max3_f32 v32, v32, v18, v19
	v_max3_f32 v32, v32, v20, v21
	v_max3_f32 v32, v32, v22, v23
	v_max3_f32 v32, v32, v24, v25
	v_max3_f32 v32, v32, v26, v27
	v_max3_f32 v32, v32, v28, v29
	v_max3_f32 v32, v32, v30, v31
	v_mov_b32_e32 v33, v32
	s_nop 1
	v_permlane32_swap_b32_e32 v32, v33
	v_max_f32_e32 v33, v33, v33
	v_max_f32_e32 v32, v32, v32
	v_max_f32_e32 v32, v32, v33
	v_add_f32_e32 v32, v37, v32
	v_add_f32_e32 v33, 0x7149f2ca, v32
	s_lshr_b32 s90, s96, 6
	s_add_i32 s4, s4, 0x18000
	v_cmp_ge_f32_e32 vcc, s35, v33
	s_cmp_eq_u64 vcc, exec
	v_max_f32_e32 v32, 0xf149f2ca, v32
	s_cselect_b64 vcc, -1, 0
	v_cndmask_b32_e32 v148, v32, v214, vcc
	v_sub_f32_e32 v33, v148, v37
	v_sub_f32_e32 v0, v0, v33
	v_exp_f32_e32 v145, v0
	v_sub_f32_e32 v0, v1, v33
	v_exp_f32_e32 v158, v0
	v_sub_f32_e32 v0, v2, v33
	v_exp_f32_e32 v146, v0
	v_sub_f32_e32 v0, v3, v33
	v_exp_f32_e32 v159, v0
	v_sub_f32_e32 v0, v4, v33
	v_exp_f32_e32 v147, v0
	v_sub_f32_e32 v0, v5, v33
	v_exp_f32_e32 v228, v0
	v_sub_f32_e32 v0, v6, v33
	v_exp_f32_e32 v157, v0
	v_sub_f32_e32 v0, v7, v33
	v_exp_f32_e32 v231, v0
	v_sub_f32_e32 v0, v8, v33
	v_exp_f32_e32 v149, v0
	v_sub_f32_e32 v0, v9, v33
	v_exp_f32_e32 v153, v0
	v_sub_f32_e32 v0, v10, v33
	v_exp_f32_e32 v150, v0
	v_sub_f32_e32 v0, v11, v33
	v_exp_f32_e32 v154, v0
	v_sub_f32_e32 v0, v12, v33
	v_sub_f32_e32 v140, v16, v33
	v_sub_f32_e32 v16, 0xf149f2ca, v32
	v_exp_f32_e32 v151, v0
	v_sub_f32_e32 v0, v13, v33
	v_exp_f32_e32 v16, v16
	v_exp_f32_e32 v155, v0
	v_sub_f32_e32 v0, v14, v33
	v_exp_f32_e32 v152, v0
	v_sub_f32_e32 v0, v15, v33
	v_exp_f32_e32 v156, v0
	v_lshl_add_u32 v215, v169, 2, s4
	v_lshl_add_u32 v179, v171, 2, s4
	s_lshl_b64 s[4:5], s[6:7], 8
	s_waitcnt vmcnt(4)
	s_add_u32 s4, s29, s4
	v_lshlrev_b32_e32 v0, 2, v36
	v_mov_b32_e32 v14, v161
	v_mov_b32_e32 v15, v161
	s_waitcnt vmcnt(7)
	ds_write_b128 v210, v[38:41] offset:16384
	s_waitcnt vmcnt(6)
	ds_write_b128 v211, v[42:45] offset:16384
	s_waitcnt vmcnt(5)
	ds_write_b128 v212, v[46:49] offset:49152
	s_waitcnt vmcnt(4)
	ds_write_b128 v213, v[50:53] offset:49152
	v_sub_f32_e32 v141, v17, v33
	v_sub_f32_e32 v142, v18, v33
	v_sub_f32_e32 v143, v19, v33
	v_sub_f32_e32 v130, v20, v33
	v_sub_f32_e32 v131, v21, v33
	v_sub_f32_e32 v132, v22, v33
	v_sub_f32_e32 v133, v23, v33
	v_sub_f32_e32 v134, v24, v33
	v_sub_f32_e32 v135, v25, v33
	v_sub_f32_e32 v138, v26, v33
	v_sub_f32_e32 v139, v27, v33
	v_sub_f32_e32 v128, v28, v33
	v_sub_f32_e32 v129, v29, v33
	v_sub_f32_e32 v136, v30, v33
	v_sub_f32_e32 v137, v31, v33
	v_cndmask_b32_e64 v224, v16, 1.0, vcc
	s_addc_u32 s5, s28, s5
	v_sub_u32_e32 v223, v188, v0
	v_mov_b32_e32 v0, v161
	v_mov_b32_e32 v1, v161
	v_mov_b32_e32 v2, v161
	v_mov_b32_e32 v3, v161
	v_mov_b32_e32 v4, v161
	v_mov_b32_e32 v5, v161
	v_mov_b32_e32 v6, v161
	v_mov_b32_e32 v7, v161
	v_mov_b32_e32 v8, v161
	v_mov_b32_e32 v9, v161
	v_mov_b32_e32 v10, v161
	v_mov_b32_e32 v11, v161
	v_mov_b32_e32 v12, v161
	v_mov_b32_e32 v13, v161
	v_mov_b64_e32 v[62:63], v[14:15]
	v_mov_b64_e32 v[46:47], v[14:15]
	v_mov_b64_e32 v[30:31], v[14:15]
	s_mov_b32 s33, 2
	v_lshl_add_u64 v[182:183], v[166:167], 0, s[4:5]
	s_sub_i32 s6, 64, s97
	v_mov_b32_e32 v216, 0
	v_mov_b64_e32 v[60:61], v[12:13]
	v_mov_b64_e32 v[58:59], v[10:11]
	v_mov_b64_e32 v[56:57], v[8:9]
	v_mov_b64_e32 v[54:55], v[6:7]
	v_mov_b64_e32 v[52:53], v[4:5]
	v_mov_b64_e32 v[50:51], v[2:3]
	v_mov_b64_e32 v[48:49], v[0:1]
	v_mov_b64_e32 v[44:45], v[12:13]
	v_mov_b64_e32 v[42:43], v[10:11]
	v_mov_b64_e32 v[40:41], v[8:9]
	v_mov_b64_e32 v[38:39], v[6:7]
	v_mov_b64_e32 v[36:37], v[4:5]
	v_mov_b64_e32 v[34:35], v[2:3]
	v_mov_b64_e32 v[32:33], v[0:1]
	v_mov_b64_e32 v[28:29], v[12:13]
	v_mov_b64_e32 v[26:27], v[10:11]
	v_mov_b64_e32 v[24:25], v[8:9]
	v_mov_b64_e32 v[22:23], v[6:7]
	v_mov_b64_e32 v[20:21], v[4:5]
	v_mov_b64_e32 v[18:19], v[2:3]
	v_mov_b64_e32 v[16:17], v[0:1]
	s_waitcnt lgkmcnt(0)
	s_barrier
	v_mov_b32_e32 v250, v148
	v_mov_b32_e32 v251, 1.0
	v_mov_b32_e32 v232, v145
	v_mov_b32_e32 v233, v158
	v_mov_b32_e32 v234, v146
	v_mov_b32_e32 v235, v159
	v_mov_b32_e32 v236, v147
	v_mov_b32_e32 v237, v228
	v_mov_b32_e32 v238, v157
	v_mov_b32_e32 v239, v231
	v_mov_b32_e32 v240, v149
	v_mov_b32_e32 v241, v153
	v_mov_b32_e32 v242, v150
	v_mov_b32_e32 v243, v154
	v_mov_b32_e32 v244, v151
	v_mov_b32_e32 v245, v155
	v_mov_b32_e32 v246, v152
	v_mov_b32_e32 v247, v156
	v_exp_f32_e32 v144, v140
	v_exp_f32_e32 v145, v141
	v_exp_f32_e32 v146, v142
	v_exp_f32_e32 v147, v143
	v_exp_f32_e32 v148, v130
	v_exp_f32_e32 v149, v131
	v_exp_f32_e32 v150, v132
	v_exp_f32_e32 v151, v133
	v_exp_f32_e32 v152, v134
	v_exp_f32_e32 v153, v135
	v_exp_f32_e32 v154, v138
	v_exp_f32_e32 v155, v139
	v_exp_f32_e32 v156, v128
	v_exp_f32_e32 v157, v129
	v_exp_f32_e32 v158, v136
	v_exp_f32_e32 v159, v137
	s_waitcnt vmcnt(2)
	ds_write_b128 v212, v[112:115] offset:32768
	ds_write_b128 v213, v[116:119] offset:32768
	s_waitcnt lgkmcnt(0)
	s_mov_b32 s4, 0xffee0000
	s_mov_b32 s5, -1
	v_lshl_add_u64 v[112:113], v[182:183], 0, s[4:5]
	global_load_dwordx4 v[112:115], v[112:113], off offset:-2048
	s_mov_b32 s4, 0xfff40000
	v_lshl_add_u64 v[116:117], v[182:183], 0, s[4:5]
	global_load_dwordx4 v[116:119], v[116:117], off offset:-2048
	v_lshrrev_b32_e32 v254, 6, v168
	s_nop 1
	v_readfirstlane_b32 s4, v254
	s_nop 3
	s_cmp_ge_u32 s4, 4
	s_cbranch_scc0 .Lmb_noprio
	s_setprio 1
; #define SBAR() __builtin_amdgcn_sched_barrier(0)
; #define SLOAD(i, k0) do { sr_[i].vs0 = *(const bf16x8*)(Vh + (size_t)((k0) + sr) * PW + sc); sr_[i].vs1 = *(const bf16x8*)(Vh + (size_t)((k0) + 32 + sr) * PW + sc); \
;     sr_[i].ks0 = *(const bf16x8*)(Kh + (size_t)((k0) + sr) * PW + sc); sr_[i].ks1 = *(const bf16x8*)(Kh + (size_t)((k0) + 32 + sr) * PW + sc); } while (0)
; __device__ __forceinline__ void partialSM(f32x16& p0, f32x16& p1, const LAS float* tbp, int relc, float cL, float cR, float& m_reg, float& mn, float& alpha) {
;     float cb = 0.f;
;     if (relc + 63 <= -559) cb = cL;
;     else if (relc - 31 >= 559) cb = cR;
; __device__ __forceinline__ void unit(LAS unsigned char* lds, const bf16* __restrict__ PROJ, bf16* __restrict__ MIXED, const float* __restrict__ subln_g, float lam, int R0, int seq, int h, int qb) {
;     ...
;     for (int j = 1; j + 1 < NT; j += 2) {
;         SBAR(); qkt(pB0, pB1, K_lds + SHM_K, qr, r32, cb0);
;         finishSM(pA0, pA1, alA, l_reg, pa0, pa1, pa2, pa3); SBAR();
;         SLOAD(SO, (j + 2) * 64); SBAR();
;         pv_d0(o, vb0, pa0, pa1, pa2, pa3); partialSM(pB0, pB1, tbq + j * 64, rc0 + j * 64, cL, cR, m_reg, mnB, alB);
.Lmb_noprio:
.Lmb_loop:
	s_add_i32 s33, s33, 2
	s_cmp_ge_u32 s33, s90
	s_cselect_b64 s[26:27], -1, 0
	s_mov_b32 s28, 0
	v_mov_b32_e32 v249, v181
	s_cmpk_lt_i32 s6, 0xfd93
	s_cbranch_scc1 .Lmb_cls_h1
	v_mov_b32_e32 v249, v217
	s_cmpk_gt_i32 s6, 0x24d
	s_cbranch_scc1 .Lmb_cls_h1
	s_mov_b32 s28, 1
	v_mov_b32_e32 v249, 0

; #define LDS_WAIT() asm volatile("s_waitcnt lgkmcnt(0)" ::: "memory")
; #define SBAR() __builtin_amdgcn_sched_barrier(0)
; __device__ __forceinline__ int crow(int r, int hi) { return (r & 3) + 8 * (r >> 2) + 4 * hi; }
; __device__ __forceinline__ float half_add(float v) { auto rr = __builtin_amdgcn_permlane32_swap(__float_as_uint(v), __float_as_uint(v), false, false); return __uint_as_float(rr[0]) + __uint_as_float(rr[1]); }
; #define RESC(a) do { if (__any((a) < 1.f)) { if (hi == 0) al_l[r32] = (a); LDS_WAIT(); \
;     _Pragma("unroll") for (int r = 0; r < 16; ++r) { const float av = al_l[crow(r, hi)]; _Pragma("unroll") for (int d = 0; d < 4; ++d) o[d][r] *= av; } } } while (0)
; __device__ __forceinline__ void finishSM(f32x16& p0, f32x16& p1, float alpha, float& l_reg, bf16x8& pa0, bf16x8& pa1, bf16x8& pa2, bf16x8& pa3) {
; #pragma unroll
;     for (int r = 0; r < 16; ++r) p1[r] = __builtin_amdgcn_exp2f(p1[r]);
;     float ps = 0;
; #pragma unroll
;     for (int r = 0; r < 16; ++r) ps += p0[r];
; #pragma unroll
;     for (int r = 0; r < 16; ++r) ps += p1[r];
;     ps = half_add(ps);
;     l_reg = l_reg * alpha + ps;
;     PK4(p0, 0, pa0); PK4(p0, 8, pa1); PK4(p1, 0, pa2); PK4(p1, 8, pa3);
; }
; __device__ __forceinline__ void unit(LAS unsigned char* lds, const bf16* __restrict__ PROJ, bf16* __restrict__ MIXED, const float* __restrict__ subln_g, float lam, int R0, int seq, int h, int qb) {
;     ...
;     __syncthreads(); RESC(alB);
;     finishSM(pB0, pB1, alB, l_reg, pa0, pa1, pa2, pa3); SBAR();
;     pv_d0(o, vb0 + SHM_V, pa0, pa1, pa2, pa3);
;     ...
;     if (hi == 0) li_l[r32] = l_reg; LDS_WAIT();
;     float rli[16];
; #pragma unroll
;     for (int r = 0; r < 16; ++r) rli[r] = __builtin_amdgcn_rcpf(li_l[crow(r, hi)]);
.Lmb_nr_pe:
	v_exp_f32_e32 v64, v64
	v_exp_f32_e32 v65, v65
	v_exp_f32_e32 v66, v66
	v_exp_f32_e32 v67, v67
	v_exp_f32_e32 v68, v68
	v_exp_f32_e32 v69, v69
	v_exp_f32_e32 v70, v70
	v_exp_f32_e32 v71, v71
	v_exp_f32_e32 v72, v72
	v_exp_f32_e32 v73, v73
	v_exp_f32_e32 v74, v74
	v_exp_f32_e32 v75, v75
	v_exp_f32_e32 v76, v76
	v_exp_f32_e32 v77, v77
	v_exp_f32_e32 v78, v78
	v_exp_f32_e32 v79, v79
	v_add_f32_e32 v254, v80, v81
	v_add_f32_e32 v255, v82, v83
	v_add_f32_e32 v254, v254, v84
	v_add_f32_e32 v255, v255, v85
	v_add_f32_e32 v254, v254, v86
	v_add_f32_e32 v255, v255, v87
	v_add_f32_e32 v254, v254, v88
	v_add_f32_e32 v255, v255, v89
	v_add_f32_e32 v254, v254, v90
	v_add_f32_e32 v255, v255, v91
	v_add_f32_e32 v254, v254, v92
	v_add_f32_e32 v255, v255, v93
	v_add_f32_e32 v254, v254, v94
	v_add_f32_e32 v255, v255, v95
	v_add_f32_e32 v254, v254, v64
	v_add_f32_e32 v255, v255, v65
	v_add_f32_e32 v254, v254, v66
	v_add_f32_e32 v255, v255, v67
	v_add_f32_e32 v254, v254, v68
	v_add_f32_e32 v255, v255, v69
	v_add_f32_e32 v254, v254, v70
	v_add_f32_e32 v255, v255, v71
	v_add_f32_e32 v254, v254, v72
	v_add_f32_e32 v255, v255, v73
	v_add_f32_e32 v254, v254, v74
	v_add_f32_e32 v255, v255, v75
	v_add_f32_e32 v254, v254, v76
	v_add_f32_e32 v255, v255, v77
	v_add_f32_e32 v254, v254, v78
	v_add_f32_e32 v255, v255, v79
	v_add_f32_e32 v254, v254, v255
	v_mov_b32_e32 v255, v254
	v_cvt_pk_bf16_f32 v80, v80, v81
	v_cvt_pk_bf16_f32 v81, v82, v83
	v_cvt_pk_bf16_f32 v82, v84, v85
	v_cvt_pk_bf16_f32 v83, v86, v87
	v_cvt_pk_bf16_f32 v84, v88, v89
	v_cvt_pk_bf16_f32 v85, v90, v91
	v_cvt_pk_bf16_f32 v86, v92, v93
	v_cvt_pk_bf16_f32 v87, v94, v95
	v_permlane32_swap_b32_e32 v254, v255
	v_cvt_pk_bf16_f32 v64, v64, v65
	v_cvt_pk_bf16_f32 v65, v66, v67
	v_cvt_pk_bf16_f32 v66, v68, v69
	v_cvt_pk_bf16_f32 v67, v70, v71
	v_cvt_pk_bf16_f32 v68, v72, v73
	v_cvt_pk_bf16_f32 v69, v74, v75
	v_cvt_pk_bf16_f32 v70, v76, v77
	v_cvt_pk_bf16_f32 v71, v78, v79
	v_add_f32_e32 v254, v254, v255
	v_fma_f32 v216, v216, v251, v254
	v_permlane32_swap_b32_e32 v80, v82
	v_permlane32_swap_b32_e32 v81, v83
	v_permlane32_swap_b32_e32 v84, v86
	v_permlane32_swap_b32_e32 v85, v87
	v_permlane32_swap_b32_e32 v64, v66
	v_permlane32_swap_b32_e32 v65, v67
	v_permlane32_swap_b32_e32 v68, v70
	v_permlane32_swap_b32_e32 v69, v71
	ds_read_b64_tr_b16 v[88:89], v186 offset:0
	ds_read_b64_tr_b16 v[90:91], v186 offset:2048
	ds_read_b64_tr_b16 v[92:93], v186 offset:4096
	ds_read_b64_tr_b16 v[94:95], v186 offset:6144
	ds_read_b64_tr_b16 v[72:73], v186 offset:8192
	ds_read_b64_tr_b16 v[74:75], v186 offset:10240
	ds_read_b64_tr_b16 v[76:77], v186 offset:12288
	ds_read_b64_tr_b16 v[78:79], v186 offset:14336
	s_waitcnt lgkmcnt(0)
	v_mfma_f32_32x32x16_bf16 v[0:15], v[80:83], v[88:91], v[0:15]
	ds_read_b64_tr_b16 v[88:89], v186 offset:512
	ds_read_b64_tr_b16 v[90:91], v186 offset:2560
	v_mfma_f32_32x32x16_bf16 v[0:15], v[84:87], v[92:95], v[0:15]
	ds_read_b64_tr_b16 v[92:93], v186 offset:4608
	ds_read_b64_tr_b16 v[94:95], v186 offset:6656
	v_mfma_f32_32x32x16_bf16 v[0:15], v[64:67], v[72:75], v[0:15]
	ds_read_b64_tr_b16 v[72:73], v186 offset:8704
	ds_read_b64_tr_b16 v[74:75], v186 offset:10752
	v_mfma_f32_32x32x16_bf16 v[0:15], v[68:71], v[76:79], v[0:15]
	ds_read_b64_tr_b16 v[76:77], v186 offset:12800
	ds_read_b64_tr_b16 v[78:79], v186 offset:14848
	s_waitcnt lgkmcnt(0)
	v_mfma_f32_32x32x16_bf16 v[48:63], v[80:83], v[88:91], v[48:63]
	ds_read_b64_tr_b16 v[88:89], v186 offset:1024
	ds_read_b64_tr_b16 v[90:91], v186 offset:3072
	v_mfma_f32_32x32x16_bf16 v[48:63], v[84:87], v[92:95], v[48:63]
	ds_read_b64_tr_b16 v[92:93], v186 offset:5120
	ds_read_b64_tr_b16 v[94:95], v186 offset:7168
	v_mfma_f32_32x32x16_bf16 v[48:63], v[64:67], v[72:75], v[48:63]
	ds_read_b64_tr_b16 v[72:73], v186 offset:9216
	ds_read_b64_tr_b16 v[74:75], v186 offset:11264
	v_mfma_f32_32x32x16_bf16 v[48:63], v[68:71], v[76:79], v[48:63]
	ds_read_b64_tr_b16 v[76:77], v186 offset:13312
	ds_read_b64_tr_b16 v[78:79], v186 offset:15360
	s_waitcnt lgkmcnt(0)
	v_mfma_f32_32x32x16_bf16 v[32:47], v[80:83], v[88:91], v[32:47]
	ds_read_b64_tr_b16 v[88:89], v186 offset:1536
	ds_read_b64_tr_b16 v[90:91], v186 offset:3584
	v_mfma_f32_32x32x16_bf16 v[32:47], v[84:87], v[92:95], v[32:47]
	ds_read_b64_tr_b16 v[92:93], v186 offset:5632
	ds_read_b64_tr_b16 v[94:95], v186 offset:7680
	v_mfma_f32_32x32x16_bf16 v[32:47], v[64:67], v[72:75], v[32:47]
	ds_read_b64_tr_b16 v[72:73], v186 offset:9728
	ds_read_b64_tr_b16 v[74:75], v186 offset:11776
	v_mfma_f32_32x32x16_bf16 v[32:47], v[68:71], v[76:79], v[32:47]
	ds_read_b64_tr_b16 v[76:77], v186 offset:13824
	ds_read_b64_tr_b16 v[78:79], v186 offset:15872
	s_waitcnt lgkmcnt(0)
	v_mfma_f32_32x32x16_bf16 v[16:31], v[80:83], v[88:91], v[16:31]
	v_mfma_f32_32x32x16_bf16 v[16:31], v[84:87], v[92:95], v[16:31]
	v_mfma_f32_32x32x16_bf16 v[16:31], v[64:67], v[72:75], v[16:31]
	v_mfma_f32_32x32x16_bf16 v[16:31], v[68:71], v[76:79], v[16:31]
	s_setprio 0
	s_and_saveexec_b64 s[4:5], s[0:1]
	ds_write_b32 v215, v216
	s_or_b64 exec, exec, s[4:5]
	s_waitcnt lgkmcnt(0)
	ds_read_b128 v[64:67], v179
	ds_read_b128 v[68:71], v179 offset:32
	s_lshl_b32 s4, s95, 14
	s_add_i32 s6, s4, 0
	s_cmp_eq_u32 s71, 0
	s_waitcnt lgkmcnt(1)
	v_rcp_f32_e32 v80, v64
	v_rcp_f32_e32 v79, v65
	v_rcp_f32_e32 v78, v66
	v_rcp_f32_e32 v102, v67
	s_waitcnt lgkmcnt(0)
	v_rcp_f32_e32 v107, v68
	ds_read_b128 v[64:67], v179 offset:64
	v_rcp_f32_e32 v106, v69
	v_rcp_f32_e32 v105, v70
	v_rcp_f32_e32 v104, v71
	ds_read_b128 v[68:71], v179 offset:96
	s_waitcnt lgkmcnt(1)
	v_rcp_f32_e32 v97, v64
	v_rcp_f32_e32 v96, v65
	v_rcp_f32_e32 v95, v66
	v_rcp_f32_e32 v94, v67
	s_waitcnt lgkmcnt(0)
	v_rcp_f32_e32 v93, v68
	v_rcp_f32_e32 v92, v69
	v_rcp_f32_e32 v91, v70
	v_rcp_f32_e32 v90, v71
	s_cselect_b64 s[4:5], -1, 0
	s_and_b64 vcc, exec, s[4:5]
	v_lshl_add_u32 v98, v190, 2, s6
	s_barrier
; #define LAS __attribute__((address_space(3)))
; __device__ __forceinline__ void unit(LAS unsigned char* lds, const bf16* __restrict__ PROJ, bf16* __restrict__ MIXED, const float* __restrict__ subln_g, float lam, int R0, int seq, int h, int qb) {
;     ...
;     LAS float* xch = (LAS float*)lds + g * 4096;
;     if (c == 1) {
; #pragma unroll
;         for (int d = 0; d < 4; ++d)
; #pragma unroll
;             for (int r = 0; r < 16; ++r) xch[(d * 16 + r) * 64 + lane] = o[d][r] * rli[r]; }
	s_cbranch_vccnz .LBB0_294
	v_mul_f32_e32 v64, v0, v80
	v_mul_f32_e32 v65, v1, v79
	ds_write2st64_b32 v98, v64, v65 offset1:1
	v_mul_f32_e32 v64, v2, v78
	v_mul_f32_e32 v65, v3, v102
	ds_write2st64_b32 v98, v64, v65 offset0:2 offset1:3
	v_mul_f32_e32 v64, v4, v107
	v_mul_f32_e32 v65, v5, v106
	ds_write2st64_b32 v98, v64, v65 offset0:4 offset1:5
	v_mul_f32_e32 v64, v6, v105
	v_mul_f32_e32 v65, v7, v104
	ds_write2st64_b32 v98, v64, v65 offset0:6 offset1:7
	v_mul_f32_e32 v64, v8, v97
	v_mul_f32_e32 v65, v9, v96
	ds_write2st64_b32 v98, v64, v65 offset0:8 offset1:9
	v_mul_f32_e32 v64, v10, v95
	v_mul_f32_e32 v65, v11, v94
	ds_write2st64_b32 v98, v64, v65 offset0:10 offset1:11
	v_mul_f32_e32 v64, v12, v93
	v_mul_f32_e32 v65, v13, v92
	ds_write2st64_b32 v98, v64, v65 offset0:12 offset1:13
	v_mul_f32_e32 v64, v14, v91
	v_mul_f32_e32 v65, v15, v90
	ds_write2st64_b32 v98, v64, v65 offset0:14 offset1:15
	v_mul_f32_e32 v64, v48, v80
	v_mul_f32_e32 v65, v49, v79
	ds_write2st64_b32 v98, v64, v65 offset0:16 offset1:17
	v_mul_f32_e32 v64, v50, v78
	v_mul_f32_e32 v65, v51, v102
	ds_write2st64_b32 v98, v64, v65 offset0:18 offset1:19
	v_mul_f32_e32 v64, v52, v107
	v_mul_f32_e32 v65, v53, v106
	ds_write2st64_b32 v98, v64, v65 offset0:20 offset1:21
	v_mul_f32_e32 v64, v54, v105
	v_mul_f32_e32 v65, v55, v104
	ds_write2st64_b32 v98, v64, v65 offset0:22 offset1:23
	v_mul_f32_e32 v64, v56, v97
	v_mul_f32_e32 v65, v57, v96
	ds_write2st64_b32 v98, v64, v65 offset0:24 offset1:25
	v_mul_f32_e32 v64, v58, v95
	v_mul_f32_e32 v65, v59, v94
	ds_write2st64_b32 v98, v64, v65 offset0:26 offset1:27
	v_mul_f32_e32 v64, v60, v93
	v_mul_f32_e32 v65, v61, v92
	ds_write2st64_b32 v98, v64, v65 offset0:28 offset1:29
	v_mul_f32_e32 v64, v62, v91
	v_mul_f32_e32 v65, v63, v90
	ds_write2st64_b32 v98, v64, v65 offset0:30 offset1:31
	v_mul_f32_e32 v64, v32, v80
	v_mul_f32_e32 v65, v33, v79
	ds_write2st64_b32 v98, v64, v65 offset0:32 offset1:33
	v_mul_f32_e32 v64, v34, v78
	v_mul_f32_e32 v65, v35, v102
	ds_write2st64_b32 v98, v64, v65 offset0:34 offset1:35
	v_mul_f32_e32 v64, v36, v107
	v_mul_f32_e32 v65, v37, v106
	ds_write2st64_b32 v98, v64, v65 offset0:36 offset1:37
	v_mul_f32_e32 v64, v38, v105
	v_mul_f32_e32 v65, v39, v104
	ds_write2st64_b32 v98, v64, v65 offset0:38 offset1:39
	v_mul_f32_e32 v64, v40, v97
	v_mul_f32_e32 v65, v41, v96
	ds_write2st64_b32 v98, v64, v65 offset0:40 offset1:41
	v_mul_f32_e32 v64, v42, v95
	v_mul_f32_e32 v65, v43, v94
	ds_write2st64_b32 v98, v64, v65 offset0:42 offset1:43
	v_mul_f32_e32 v64, v44, v93
	v_mul_f32_e32 v65, v45, v92
	ds_write2st64_b32 v98, v64, v65 offset0:44 offset1:45
	v_mul_f32_e32 v64, v46, v91
	v_mul_f32_e32 v65, v47, v90
	ds_write2st64_b32 v98, v64, v65 offset0:46 offset1:47
	v_mul_f32_e32 v64, v16, v80
	v_mul_f32_e32 v65, v17, v79
	ds_write2st64_b32 v98, v64, v65 offset0:48 offset1:49
	v_mul_f32_e32 v64, v18, v78
	v_mul_f32_e32 v65, v19, v102
	ds_write2st64_b32 v98, v64, v65 offset0:50 offset1:51
	v_mul_f32_e32 v64, v20, v107
	v_mul_f32_e32 v65, v21, v106
	ds_write2st64_b32 v98, v64, v65 offset0:52 offset1:53
	v_mul_f32_e32 v64, v22, v105
	v_mul_f32_e32 v65, v23, v104
	ds_write2st64_b32 v98, v64, v65 offset0:54 offset1:55
	v_mul_f32_e32 v64, v24, v97
	v_mul_f32_e32 v65, v25, v96
	ds_write2st64_b32 v98, v64, v65 offset0:56 offset1:57
	v_mul_f32_e32 v64, v26, v95
	v_mul_f32_e32 v65, v27, v94
	ds_write2st64_b32 v98, v64, v65 offset0:58 offset1:59
	v_mul_f32_e32 v64, v28, v93
	v_mul_f32_e32 v65, v29, v92
	ds_write2st64_b32 v98, v64, v65 offset0:60 offset1:61
	v_mul_f32_e32 v64, v30, v91
	v_mul_f32_e32 v65, v31, v90
	ds_write2st64_b32 v98, v64, v65 offset0:62 offset1:63
